# back-edge rotation on mixer-A tile loop with the loop body pinned to a 32-byte boundary
# speedup vs baseline: 1.0058x; 1.0058x over previous
.Lattn_prio_skip_a:
	s_mov_b32 s7, 0
	.p2align 5
	s_nop 0
	s_nop 0
	s_nop 0
	s_nop 0
	s_nop 0
	s_nop 0
	s_nop 0
